# v16: as v14 but the DA P*V section reads its V fragments four ahead of the MFMAs (v240-255) instead of keeping the Q fragments in those registers
# speedup vs baseline: 1.0671x; 1.0036x over previous
; #define MFMA32(a, b, c) __builtin_amdgcn_mfma_f32_32x32x16_bf16((a), (b), (c), 0, 0, 0)
; DI void da_item(const Params& P, int layer, int b, int h, int qt, char* mb, char* smem) {
;     ...
;         float ls = 0.f;
; #pragma unroll
;         for (int kb = 0; kb < 2; kb++)
; #pragma unroll
;           for (int i = 0; i < 16; i++) { const float p = __builtin_amdgcn_exp2f(s[kb][i] - mn); s[kb][i] = p; ls += p; }
;         l = l * corr + ls;
;         if (__ballot(corr != 1.f) != 0ull) {
; #pragma unroll
;           for (int dt = 0; dt < 4; dt++)
; #pragma unroll
;             for (int i = 0; i < 16; i++) o[dt][i] *= corr;
;         }
; #pragma unroll
;         for (int kb = 0; kb < 2; kb++)
; #pragma unroll
;           for (int s2 = 0; s2 < 2; s2++) {
;             const bf16x8 pf = pack8(s[kb], s2);
; #pragma unroll
;             for (int dt = 0; dt < 4; dt++) {
;               const u16* vp = sV + (dt * 32 + r) * VS_ + kb * 32 + s2 * 16 + 4 * hh;
;               const s16x4 lo = *(const s16x4*)vp, hi = *(const s16x4*)(vp + 8);
;               const bf16x8 vf = __builtin_shufflevector(lo, hi, 0, 1, 2, 3, 4, 5, 6, 7);
;               o[dt] = MFMA32(vf, pf, o[dt]);
;             }
;             __builtin_amdgcn_sched_barrier(0);
;           }
.LBB0_4127:
	v_sub_f32_e32 v4, v4, v3
	v_exp_f32_e32 v83, v4
	v_sub_f32_e32 v4, v5, v3
	v_exp_f32_e32 v84, v4
	v_sub_f32_e32 v4, v6, v3
	v_exp_f32_e32 v85, v4
	v_sub_f32_e32 v4, v7, v3
	v_exp_f32_e32 v86, v4
	v_sub_f32_e32 v5, v8, v3
	v_add_f32_e32 v4, 0, v83
	v_exp_f32_e32 v87, v5
	v_sub_f32_e32 v5, v9, v3
	v_add_f32_e32 v4, v84, v4
	v_exp_f32_e32 v88, v5
	v_sub_f32_e32 v5, v10, v3
	v_add_f32_e32 v4, v85, v4
	v_exp_f32_e32 v89, v5
	v_sub_f32_e32 v5, v11, v3
	v_add_f32_e32 v4, v86, v4
	v_exp_f32_e32 v11, v5
	v_sub_f32_e32 v5, v12, v3
	v_add_f32_e32 v4, v87, v4
	v_exp_f32_e32 v90, v5
	v_sub_f32_e32 v5, v13, v3
	v_add_f32_e32 v4, v88, v4
	v_exp_f32_e32 v91, v5
	v_sub_f32_e32 v5, v14, v3
	v_add_f32_e32 v4, v89, v4
	v_exp_f32_e32 v92, v5
	v_sub_f32_e32 v5, v15, v3
	v_add_f32_e32 v4, v11, v4
	v_exp_f32_e32 v93, v5
	v_sub_f32_e32 v5, v16, v3
	v_add_f32_e32 v4, v90, v4
	v_exp_f32_e32 v16, v5
	v_sub_f32_e32 v5, v17, v3
	v_add_f32_e32 v4, v91, v4
	v_exp_f32_e32 v17, v5
	v_sub_f32_e32 v5, v184, v3
	v_add_f32_e32 v4, v92, v4
	v_exp_f32_e32 v94, v5
	v_sub_f32_e32 v5, v185, v3
	v_add_f32_e32 v4, v93, v4
	v_exp_f32_e32 v95, v5
	v_sub_f32_e32 v5, v186, v3
	v_add_f32_e32 v4, v16, v4
	v_exp_f32_e32 v96, v5
	v_sub_f32_e32 v5, v187, v3
	v_add_f32_e32 v4, v17, v4
	v_exp_f32_e32 v97, v5
	v_sub_f32_e32 v5, v188, v3
	v_add_f32_e32 v4, v94, v4
	v_exp_f32_e32 v98, v5
	v_sub_f32_e32 v5, v189, v3
	v_add_f32_e32 v4, v95, v4
	v_exp_f32_e32 v99, v5
	v_sub_f32_e32 v5, v190, v3
	v_add_f32_e32 v4, v96, v4
	v_exp_f32_e32 v100, v5
	v_sub_f32_e32 v5, v191, v3
	v_add_f32_e32 v4, v97, v4
	v_exp_f32_e32 v101, v5
	v_sub_f32_e32 v5, v192, v3
	v_add_f32_e32 v4, v98, v4
	v_exp_f32_e32 v102, v5
	v_sub_f32_e32 v5, v193, v3
	v_add_f32_e32 v4, v99, v4
	v_exp_f32_e32 v103, v5
	v_add_f32_e32 v4, v100, v4
	v_add_f32_e32 v4, v101, v4
	v_add_f32_e32 v4, v102, v4
	v_add_f32_e32 v104, v103, v4
	v_sub_f32_e32 v4, v200, v3
	s_mulk_i32 s43, 0x4400
	v_exp_f32_e32 v105, v4
	v_sub_f32_e32 v4, v201, v3
	v_add3_u32 v108, v216, s43, v221
	v_exp_f32_e32 v106, v4
	v_sub_f32_e32 v4, v198, v3
	v_add_u32_e32 v109, 0x4800, v108
	v_sub_f32_e32 v8, v199, v3
	v_exp_f32_e32 v107, v4
	ds_read2_b64 v[4:7], v109 offset1:2
	v_exp_f32_e32 v110, v8
	v_cvt_pk_bf16_f32 v8, v83, v84
	v_add_u32_e32 v83, 0x5800, v108
	ds_read2_b64 v[12:15], v83 offset0:32 offset1:34
	v_cvt_pk_bf16_f32 v9, v85, v86
	v_cvt_pk_bf16_f32 v10, v87, v88
	v_cvt_pk_bf16_f32 v11, v89, v11
	v_add_u32_e32 v86, 0x6800, v108
	v_add_u32_e32 v89, 0x7800, v108
	s_waitcnt lgkmcnt(1)
	v_mfma_f32_32x32x16_bf16 v[66:81], v[4:7], v[8:11], v[66:81]
	v_add_f32_e32 v4, v105, v104
	v_add_f32_e32 v4, v106, v4
	v_add_f32_e32 v4, v107, v4
	v_add_f32_e32 v84, v110, v4
	ds_read2_b64 v[4:7], v86 offset0:64 offset1:66
	v_sub_f32_e32 v85, v196, v3
	v_exp_f32_e32 v85, v85
	s_waitcnt lgkmcnt(1)
	v_mfma_f32_32x32x16_bf16 v[50:65], v[12:15], v[8:11], v[50:65]
	v_sub_f32_e32 v12, v197, v3
	v_exp_f32_e32 v87, v12
	v_sub_f32_e32 v12, v194, v3
	v_exp_f32_e32 v88, v12
	ds_read2_b64 v[12:15], v89 offset0:96 offset1:98
	s_waitcnt lgkmcnt(1)
	v_mfma_f32_32x32x16_bf16 v[34:49], v[4:7], v[8:11], v[34:49]
	v_sub_f32_e32 v4, v195, v3
	v_exp_f32_e32 v104, v4
	v_add_f32_e32 v4, v85, v84
	v_add_f32_e32 v4, v87, v4
	v_add_f32_e32 v4, v88, v4
	v_add_f32_e32 v84, v104, v4
	v_fmac_f32_e32 v84, v225, v82
	s_waitcnt lgkmcnt(0)
	v_mfma_f32_32x32x16_bf16 v[18:33], v[12:15], v[8:11], v[18:33]
	ds_read2_b64 v[4:7], v109 offset0:4 offset1:6
	ds_read2_b64 v[12:15], v83 offset0:36 offset1:38
	ds_read2_b64 v[240:243], v86 offset0:68 offset1:70
	ds_read2_b64 v[244:247], v89 offset0:100 offset1:102
	v_cvt_pk_bf16_f32 v8, v90, v91
	v_cvt_pk_bf16_f32 v9, v92, v93
	v_cvt_pk_bf16_f32 v10, v16, v17
	v_cvt_pk_bf16_f32 v11, v94, v95
	s_waitcnt lgkmcnt(3)
	s_nop 0
	v_mfma_f32_32x32x16_bf16 v[66:81], v[4:7], v[8:11], v[66:81]
	ds_read2_b64 v[248:251], v109 offset0:8 offset1:10
	s_waitcnt lgkmcnt(3)
	v_mfma_f32_32x32x16_bf16 v[50:65], v[12:15], v[8:11], v[50:65]
	ds_read2_b64 v[252:255], v83 offset0:40 offset1:42
	s_waitcnt lgkmcnt(3)
	v_mfma_f32_32x32x16_bf16 v[34:49], v[240:243], v[8:11], v[34:49]
	ds_read2_b64 v[4:7], v86 offset0:72 offset1:74
	s_waitcnt lgkmcnt(3)
	v_mfma_f32_32x32x16_bf16 v[18:33], v[244:247], v[8:11], v[18:33]
	ds_read2_b64 v[12:15], v89 offset0:104 offset1:106
	v_cvt_pk_bf16_f32 v8, v96, v97
	v_cvt_pk_bf16_f32 v9, v98, v99
	v_cvt_pk_bf16_f32 v10, v100, v101
	v_cvt_pk_bf16_f32 v11, v102, v103
	s_waitcnt lgkmcnt(3)
	s_nop 0
	v_mfma_f32_32x32x16_bf16 v[66:81], v[248:251], v[8:11], v[66:81]
	ds_read2_b64 v[240:243], v109 offset0:12 offset1:14
	s_waitcnt lgkmcnt(3)
	v_mfma_f32_32x32x16_bf16 v[50:65], v[252:255], v[8:11], v[50:65]
	ds_read2_b64 v[244:247], v83 offset0:44 offset1:46
	s_waitcnt lgkmcnt(3)
	v_mfma_f32_32x32x16_bf16 v[34:49], v[4:7], v[8:11], v[34:49]
	ds_read2_b64 v[248:251], v86 offset0:76 offset1:78
	s_waitcnt lgkmcnt(3)
	v_mfma_f32_32x32x16_bf16 v[18:33], v[12:15], v[8:11], v[18:33]
	ds_read2_b64 v[252:255], v89 offset0:108 offset1:110
	v_cvt_pk_bf16_f32 v8, v105, v106
	v_cvt_pk_bf16_f32 v9, v107, v110
	v_cvt_pk_bf16_f32 v10, v85, v87
	v_cvt_pk_bf16_f32 v11, v88, v104
	s_waitcnt lgkmcnt(3)
	s_nop 0
	v_mfma_f32_32x32x16_bf16 v[66:81], v[240:243], v[8:11], v[66:81]
	s_waitcnt lgkmcnt(2)
	v_mfma_f32_32x32x16_bf16 v[50:65], v[244:247], v[8:11], v[50:65]
	s_waitcnt lgkmcnt(1)
	v_mfma_f32_32x32x16_bf16 v[34:49], v[248:251], v[8:11], v[34:49]
	s_waitcnt lgkmcnt(0)
	v_mfma_f32_32x32x16_bf16 v[18:33], v[252:255], v[8:11], v[18:33]
	v_mov_b32_e32 v226, v3
	v_mov_b32_e32 v225, v84

; #define MFMA32(a, b, c) __builtin_amdgcn_mfma_f32_32x32x16_bf16((a), (b), (c), 0, 0, 0)
; DI void da_item(const Params& P, int layer, int b, int h, int qt, char* mb, char* smem) {
;     ...
;         float ls = 0.f;
; #pragma unroll
;         for (int kb = 0; kb < 2; kb++)
; #pragma unroll
;           for (int i = 0; i < 16; i++) { const float p = __builtin_amdgcn_exp2f(s[kb][i] - mn); s[kb][i] = p; ls += p; }
;         l = l * corr + ls;
;         if (__ballot(corr != 1.f) != 0ull) {
; #pragma unroll
;           for (int dt = 0; dt < 4; dt++)
; #pragma unroll
;             for (int i = 0; i < 16; i++) o[dt][i] *= corr;
;         }
; #pragma unroll
;         for (int kb = 0; kb < 2; kb++)
; #pragma unroll
;           for (int s2 = 0; s2 < 2; s2++) {
;             const bf16x8 pf = pack8(s[kb], s2);
; #pragma unroll
;             for (int dt = 0; dt < 4; dt++) {
;               const u16* vp = sV + (dt * 32 + r) * VS_ + kb * 32 + s2 * 16 + 4 * hh;
;               const s16x4 lo = *(const s16x4*)vp, hi = *(const s16x4*)(vp + 8);
;               const bf16x8 vf = __builtin_shufflevector(lo, hi, 0, 1, 2, 3, 4, 5, 6, 7);
;               o[dt] = MFMA32(vf, pf, o[dt]);
;             }
;             __builtin_amdgcn_sched_barrier(0);
;           }
.LBB0_8086:
	v_sub_f32_e32 v4, v4, v3
	v_exp_f32_e32 v83, v4
	v_sub_f32_e32 v4, v5, v3
	v_exp_f32_e32 v84, v4
	v_sub_f32_e32 v4, v6, v3
	v_exp_f32_e32 v85, v4
	v_sub_f32_e32 v4, v7, v3
	v_exp_f32_e32 v86, v4
	v_sub_f32_e32 v5, v8, v3
	v_add_f32_e32 v4, 0, v83
	v_exp_f32_e32 v87, v5
	v_sub_f32_e32 v5, v9, v3
	v_add_f32_e32 v4, v84, v4
	v_exp_f32_e32 v88, v5
	v_sub_f32_e32 v5, v10, v3
	v_add_f32_e32 v4, v85, v4
	v_exp_f32_e32 v89, v5
	v_sub_f32_e32 v5, v11, v3
	v_add_f32_e32 v4, v86, v4
	v_exp_f32_e32 v11, v5
	v_sub_f32_e32 v5, v12, v3
	v_add_f32_e32 v4, v87, v4
	v_exp_f32_e32 v90, v5
	v_sub_f32_e32 v5, v13, v3
	v_add_f32_e32 v4, v88, v4
	v_exp_f32_e32 v91, v5
	v_sub_f32_e32 v5, v14, v3
	v_add_f32_e32 v4, v89, v4
	v_exp_f32_e32 v92, v5
	v_sub_f32_e32 v5, v15, v3
	v_add_f32_e32 v4, v11, v4
	v_exp_f32_e32 v93, v5
	v_sub_f32_e32 v5, v16, v3
	v_add_f32_e32 v4, v90, v4
	v_exp_f32_e32 v16, v5
	v_sub_f32_e32 v5, v17, v3
	v_add_f32_e32 v4, v91, v4
	v_exp_f32_e32 v17, v5
	v_sub_f32_e32 v5, v184, v3
	v_add_f32_e32 v4, v92, v4
	v_exp_f32_e32 v94, v5
	v_sub_f32_e32 v5, v185, v3
	v_add_f32_e32 v4, v93, v4
	v_exp_f32_e32 v95, v5
	v_sub_f32_e32 v5, v186, v3
	v_add_f32_e32 v4, v16, v4
	v_exp_f32_e32 v96, v5
	v_sub_f32_e32 v5, v187, v3
	v_add_f32_e32 v4, v17, v4
	v_exp_f32_e32 v97, v5
	v_sub_f32_e32 v5, v188, v3
	v_add_f32_e32 v4, v94, v4
	v_exp_f32_e32 v98, v5
	v_sub_f32_e32 v5, v189, v3
	v_add_f32_e32 v4, v95, v4
	v_exp_f32_e32 v99, v5
	v_sub_f32_e32 v5, v190, v3
	v_add_f32_e32 v4, v96, v4
	v_exp_f32_e32 v100, v5
	v_sub_f32_e32 v5, v191, v3
	v_add_f32_e32 v4, v97, v4
	v_exp_f32_e32 v101, v5
	v_sub_f32_e32 v5, v192, v3
	v_add_f32_e32 v4, v98, v4
	v_exp_f32_e32 v102, v5
	v_sub_f32_e32 v5, v193, v3
	v_add_f32_e32 v4, v99, v4
	v_exp_f32_e32 v103, v5
	v_add_f32_e32 v4, v100, v4
	v_add_f32_e32 v4, v101, v4
	v_add_f32_e32 v4, v102, v4
	v_add_f32_e32 v104, v103, v4
	v_sub_f32_e32 v4, v200, v3
	s_mulk_i32 s44, 0x4400
	v_exp_f32_e32 v105, v4
	v_sub_f32_e32 v4, v201, v3
	v_add3_u32 v108, v217, s44, v222
	v_exp_f32_e32 v106, v4
	v_sub_f32_e32 v4, v198, v3
	v_add_u32_e32 v109, 0x4800, v108
	v_sub_f32_e32 v8, v199, v3
	v_exp_f32_e32 v107, v4
	ds_read2_b64 v[4:7], v109 offset1:2
	v_exp_f32_e32 v110, v8
	v_cvt_pk_bf16_f32 v8, v83, v84
	v_add_u32_e32 v83, 0x5800, v108
	ds_read2_b64 v[12:15], v83 offset0:32 offset1:34
	v_cvt_pk_bf16_f32 v9, v85, v86
	v_cvt_pk_bf16_f32 v10, v87, v88
	v_cvt_pk_bf16_f32 v11, v89, v11
	v_add_u32_e32 v86, 0x6800, v108
	v_add_u32_e32 v89, 0x7800, v108
	s_waitcnt lgkmcnt(1)
	v_mfma_f32_32x32x16_bf16 v[66:81], v[4:7], v[8:11], v[66:81]
	v_add_f32_e32 v4, v105, v104
	v_add_f32_e32 v4, v106, v4
	v_add_f32_e32 v4, v107, v4
	v_add_f32_e32 v84, v110, v4
	ds_read2_b64 v[4:7], v86 offset0:64 offset1:66
	v_sub_f32_e32 v85, v196, v3
	v_exp_f32_e32 v85, v85
	s_waitcnt lgkmcnt(1)
	v_mfma_f32_32x32x16_bf16 v[50:65], v[12:15], v[8:11], v[50:65]
	v_sub_f32_e32 v12, v197, v3
	v_exp_f32_e32 v87, v12
	v_sub_f32_e32 v12, v194, v3
	v_exp_f32_e32 v88, v12
	ds_read2_b64 v[12:15], v89 offset0:96 offset1:98
	s_waitcnt lgkmcnt(1)
	v_mfma_f32_32x32x16_bf16 v[34:49], v[4:7], v[8:11], v[34:49]
	v_sub_f32_e32 v4, v195, v3
	v_exp_f32_e32 v104, v4
	v_add_f32_e32 v4, v85, v84
	v_add_f32_e32 v4, v87, v4
	v_add_f32_e32 v4, v88, v4
	v_add_f32_e32 v84, v104, v4
	v_fmac_f32_e32 v84, v226, v82
	s_waitcnt lgkmcnt(0)
	v_mfma_f32_32x32x16_bf16 v[18:33], v[12:15], v[8:11], v[18:33]
	ds_read2_b64 v[4:7], v109 offset0:4 offset1:6
	ds_read2_b64 v[12:15], v83 offset0:36 offset1:38
	ds_read2_b64 v[240:243], v86 offset0:68 offset1:70
	ds_read2_b64 v[244:247], v89 offset0:100 offset1:102
	v_cvt_pk_bf16_f32 v8, v90, v91
	v_cvt_pk_bf16_f32 v9, v92, v93
	v_cvt_pk_bf16_f32 v10, v16, v17
	v_cvt_pk_bf16_f32 v11, v94, v95
	s_waitcnt lgkmcnt(3)
	s_nop 0
	v_mfma_f32_32x32x16_bf16 v[66:81], v[4:7], v[8:11], v[66:81]
	ds_read2_b64 v[248:251], v109 offset0:8 offset1:10
	s_waitcnt lgkmcnt(3)
	v_mfma_f32_32x32x16_bf16 v[50:65], v[12:15], v[8:11], v[50:65]
	ds_read2_b64 v[252:255], v83 offset0:40 offset1:42
	s_waitcnt lgkmcnt(3)
	v_mfma_f32_32x32x16_bf16 v[34:49], v[240:243], v[8:11], v[34:49]
	ds_read2_b64 v[4:7], v86 offset0:72 offset1:74
	s_waitcnt lgkmcnt(3)
	v_mfma_f32_32x32x16_bf16 v[18:33], v[244:247], v[8:11], v[18:33]
	ds_read2_b64 v[12:15], v89 offset0:104 offset1:106
	v_cvt_pk_bf16_f32 v8, v96, v97
	v_cvt_pk_bf16_f32 v9, v98, v99
	v_cvt_pk_bf16_f32 v10, v100, v101
	v_cvt_pk_bf16_f32 v11, v102, v103
	s_waitcnt lgkmcnt(3)
	s_nop 0
	v_mfma_f32_32x32x16_bf16 v[66:81], v[248:251], v[8:11], v[66:81]
	ds_read2_b64 v[240:243], v109 offset0:12 offset1:14
	s_waitcnt lgkmcnt(3)
	v_mfma_f32_32x32x16_bf16 v[50:65], v[252:255], v[8:11], v[50:65]
	ds_read2_b64 v[244:247], v83 offset0:44 offset1:46
	s_waitcnt lgkmcnt(3)
	v_mfma_f32_32x32x16_bf16 v[34:49], v[4:7], v[8:11], v[34:49]
	ds_read2_b64 v[248:251], v86 offset0:76 offset1:78
	s_waitcnt lgkmcnt(3)
	v_mfma_f32_32x32x16_bf16 v[18:33], v[12:15], v[8:11], v[18:33]
	ds_read2_b64 v[252:255], v89 offset0:108 offset1:110
	v_cvt_pk_bf16_f32 v8, v105, v106
	v_cvt_pk_bf16_f32 v9, v107, v110
	v_cvt_pk_bf16_f32 v10, v85, v87
	v_cvt_pk_bf16_f32 v11, v88, v104
	s_waitcnt lgkmcnt(3)
	s_nop 0
	v_mfma_f32_32x32x16_bf16 v[66:81], v[240:243], v[8:11], v[66:81]
	s_waitcnt lgkmcnt(2)
	v_mfma_f32_32x32x16_bf16 v[50:65], v[244:247], v[8:11], v[50:65]
	s_waitcnt lgkmcnt(1)
	v_mfma_f32_32x32x16_bf16 v[34:49], v[248:251], v[8:11], v[34:49]
	s_waitcnt lgkmcnt(0)
	v_mfma_f32_32x32x16_bf16 v[18:33], v[252:255], v[8:11], v[18:33]
	v_mov_b32_e32 v227, v3
	v_mov_b32_e32 v226, v84
